# per-XCD (per-batch) P2 work queues + fox_scan remap: seams S1,S2,S4-S6 XCD-local, S3 global w/o fences, HGRN handoff fences dropped; placement-checked fallback
# speedup vs baseline: 1.0205x; 1.0205x over previous
.Lflag_done:
	s_cmp_lt_i32 s27, 0
	s_cselect_b64 s[4:5], -1, 0
	s_cmp_gt_i32 s27, -1
	s_cselect_b64 s[0:1], -1, 0
	s_add_u32 s40, s76, 0x7c00000
	s_addc_u32 s41, s77, 0
	s_cmp_lg_u32 s27, 1
	s_cselect_b64 s[6:7], -1, 0
	s_and_b64 s[0:1], s[0:1], s[6:7]
	s_and_b64 vcc, exec, s[0:1]
	s_cbranch_vccnz .LBB0_256
	v_mov_b32_e32 v0, 0
	v_mov_b32_e32 v22, 0
	v_mbcnt_lo_u32_b32 v0, -1, v0
	v_mbcnt_hi_u32_b32 v0, -1, v0
	v_add_u32_e32 v23, s33, v0
	s_cmp_gt_u32 s2, 63
	v_readfirstlane_b32 s8, v23
	s_cbranch_scc1 .LBB0_151
	s_mov_b32 s98, s2
	s_cmp_eq_u32 s99, 0
	s_cbranch_scc1 .Lfs_done
	s_and_b32 s98, s2, 7
	s_lshl_b32 s98, s98, 3
	s_lshr_b32 s100, s2, 3
	s_or_b32 s98, s98, s100
.Lfs_done:
	s_lshl_b32 s0, s98, 12
	s_mov_b32 s1, 0
	s_ashr_i32 s9, s8, 6
	s_lshl_b64 s[6:7], s[0:1], 2
	s_add_u32 s6, s76, s6
	v_lshlrev_b32_e32 v2, 3, v23
	s_addc_u32 s7, s77, s7
	v_ashrrev_i32_e32 v3, 31, v2
	v_lshl_add_u64 v[0:1], v[2:3], 2, s[6:7]
	v_add_co_u32_e32 v4, vcc, 0x2440000, v0
	s_mov_b64 s[6:7], 0x2440000
	s_nop 0
	v_addc_co_u32_e32 v5, vcc, 0, v1, vcc
	global_load_dwordx4 v[4:7], v[4:5], off
	v_lshl_add_u64 v[0:1], v[0:1], 0, s[6:7]
	global_load_dwordx4 v[8:11], v[0:1], off offset:16
	v_mbcnt_lo_u32_b32 v0, -1, 0
	v_mbcnt_hi_u32_b32 v25, -1, v0
	v_and_b32_e32 v30, 64, v25
	v_add_u32_e32 v0, -1, v25
	v_cmp_lt_i32_e32 vcc, v0, v30
	v_and_b32_e32 v24, 63, v23
	s_waitcnt vmcnt(1)
	v_cvt_f64_f32_e32 v[12:13], v6
	v_cndmask_b32_e32 v0, v0, v25, vcc
	v_lshlrev_b32_e32 v31, 2, v0
	v_cvt_f64_f32_e32 v[0:1], v4
	v_cvt_f64_f32_e32 v[4:5], v5
	v_add_f64 v[0:1], v[0:1], 0
	v_add_f64 v[16:17], v[0:1], v[4:5]
	v_cvt_f64_f32_e32 v[6:7], v7
	v_add_f64 v[12:13], v[16:17], v[12:13]
	s_waitcnt vmcnt(0)
	v_cvt_f64_f32_e32 v[18:19], v8
	v_add_f64 v[14:15], v[12:13], v[6:7]
	v_cvt_f64_f32_e32 v[20:21], v9
	v_add_f64 v[8:9], v[14:15], v[18:19]
	v_cvt_f64_f32_e32 v[26:27], v10
	v_cvt_f64_f32_e32 v[28:29], v11
	v_add_f64 v[10:11], v[8:9], v[20:21]
	v_add_f64 v[4:5], v[10:11], v[26:27]
	v_add_f64 v[6:7], v[4:5], v[28:29]
	ds_bpermute_b32 v18, v31, v6
	ds_bpermute_b32 v19, v31, v7
	v_add_u32_e32 v20, -2, v25
	v_cmp_lt_i32_e32 vcc, v20, v30
	v_add_u32_e32 v26, -4, v25
	s_waitcnt lgkmcnt(0)
	v_add_f64 v[18:19], v[6:7], v[18:19]
	v_cndmask_b32_e32 v20, v20, v25, vcc
	v_cmp_eq_u32_e32 vcc, 0, v24
	v_lshlrev_b32_e32 v21, 2, v20
	s_nop 0
	v_cndmask_b32_e32 v19, v19, v7, vcc
	v_cndmask_b32_e32 v18, v18, v6, vcc
	ds_bpermute_b32 v20, v21, v18
	ds_bpermute_b32 v21, v21, v19
	v_cmp_lt_i32_e32 vcc, v26, v30
	s_waitcnt lgkmcnt(0)
	v_add_f64 v[20:21], v[18:19], v[20:21]
	v_cndmask_b32_e32 v26, v26, v25, vcc
	v_cmp_gt_u32_e32 vcc, 2, v24
	v_lshlrev_b32_e32 v26, 2, v26
	s_nop 0
	v_cndmask_b32_e32 v19, v21, v19, vcc
	v_cndmask_b32_e32 v18, v20, v18, vcc
	ds_bpermute_b32 v20, v26, v18
	ds_bpermute_b32 v21, v26, v19
	v_add_u32_e32 v26, -8, v25
	v_cmp_lt_i32_e32 vcc, v26, v30
	s_waitcnt lgkmcnt(0)
	v_add_f64 v[20:21], v[18:19], v[20:21]
	v_cndmask_b32_e32 v26, v26, v25, vcc
	v_cmp_gt_u32_e32 vcc, 4, v24
	v_lshlrev_b32_e32 v26, 2, v26
	s_nop 0
	v_cndmask_b32_e32 v19, v21, v19, vcc
	v_cndmask_b32_e32 v18, v20, v18, vcc
	ds_bpermute_b32 v20, v26, v18
	ds_bpermute_b32 v21, v26, v19
	v_add_u32_e32 v26, -16, v25
	v_cmp_lt_i32_e32 vcc, v26, v30
	s_waitcnt lgkmcnt(0)
	v_add_f64 v[20:21], v[18:19], v[20:21]
	v_cndmask_b32_e32 v26, v26, v25, vcc
	v_cmp_gt_u32_e32 vcc, 8, v24
	v_lshlrev_b32_e32 v26, 2, v26
	s_nop 0
	v_cndmask_b32_e32 v19, v21, v19, vcc
	v_cndmask_b32_e32 v18, v20, v18, vcc
	ds_bpermute_b32 v20, v26, v18
	ds_bpermute_b32 v21, v26, v19
	v_subrev_u32_e32 v26, 32, v25
	v_cmp_lt_i32_e32 vcc, v26, v30
	s_waitcnt lgkmcnt(0)
	v_add_f64 v[20:21], v[18:19], v[20:21]
	v_cndmask_b32_e32 v25, v26, v25, vcc
	v_cmp_gt_u32_e32 vcc, 16, v24
	v_lshlrev_b32_e32 v25, 2, v25
	s_nop 0
	v_cndmask_b32_e32 v19, v21, v19, vcc
	v_cndmask_b32_e32 v18, v20, v18, vcc
	ds_bpermute_b32 v20, v25, v18
	ds_bpermute_b32 v21, v25, v19
	v_cmp_eq_u32_e32 vcc, 63, v24
	s_waitcnt lgkmcnt(0)
	v_add_f64 v[20:21], v[18:19], v[20:21]
	s_and_saveexec_b64 s[6:7], vcc
	s_lshl_b32 s10, s9, 3
	s_add_i32 s10, s10, 0
	v_mov_b32_e32 v25, s10
	ds_write_b64 v25, v[20:21]
	s_or_b64 exec, exec, s[6:7]
	v_cmp_gt_u32_e32 vcc, 32, v24
	s_cmp_lt_i32 s9, 1
	s_waitcnt lgkmcnt(0)
	v_cndmask_b32_e32 v19, v21, v19, vcc
	v_cndmask_b32_e32 v18, v20, v18, vcc
	v_add_f64 v[18:19], v[18:19], -v[6:7]
	s_barrier
	s_cbranch_scc1 .LBB0_138
	s_cmp_lt_u32 s9, 8
	s_cbranch_scc1 .LBB0_135
	s_and_b32 s6, s9, 0x7ffffff8
	s_mov_b32 s7, 0
	s_mov_b32 s9, 0

.LBB0_149:
	s_or_b64 exec, exec, s[6:7]
	v_lshl_add_u32 v2, s98, 4, v23
	v_ashrrev_i32_e32 v3, 31, v2
	v_lshl_add_u64 v[2:3], v[2:3], 2, s[76:77]
	v_add_co_u32_e32 v2, vcc, 0x23c0000, v2
	s_nop 1
	v_addc_co_u32_e32 v3, vcc, 0, v3, vcc
	global_store_dword v[2:3], v0, off

.LBB0_202:
	s_waitcnt vmcnt(0)
	v_readlane_b32 s27, v255, 0
	s_barrier
.LBB0_203:
	s_cmp_eq_u32 s99, 0
	s_cbranch_scc1 .Lfull_1
	s_waitcnt vmcnt(0) lgkmcnt(0)
	s_barrier
	s_cmp_lg_u32 s33, 0
	s_cbranch_scc1 .Lls_join_1
	s_mov_b64 exec, 1
	s_add_i32 s98, 0, 0x25fd0
	v_mov_b32_e32 v0, s98
	ds_read_b32 v2, v0
	s_getreg_b32 s98, hwreg(HW_REG_XCC_ID, 0, 4)
	s_and_b32 s98, s98, 15
	s_lshl_b32 s98, s98, 8
	s_add_u32 s100, s76, s98
	s_addc_u32 s101, s77, 0
	v_mov_b32_e32 v0, 0xc000
	v_mov_b32_e32 v1, 1
	global_atomic_add v0, v1, s[100:101]
	s_waitcnt lgkmcnt(0)
	v_mul_lo_u32 v2, v2, 1
	s_mov_b32 s98, 0

.Lls_join_1:
	s_barrier
	s_branch .LBB0_256
.Lfull_1:
	v_mov_b32_e32 v0, 0
	s_nop 0
	v_mbcnt_lo_u32_b32 v0, -1, v0
	v_mbcnt_hi_u32_b32 v0, -1, v0
	v_add_u32_e32 v0, s33, v0
	s_waitcnt vmcnt(0)
	s_waitcnt vmcnt(0) lgkmcnt(0)
	v_cmp_eq_u32_e32 vcc, 0, v0
	s_barrier
	s_and_saveexec_b64 s[0:1], vcc
	s_cbranch_execz .LBB0_255
	s_add_i32 s7, 0, 0x25fd0
	v_mov_b32_e32 v0, s7
	s_getreg_b32 s6, hwreg(HW_REG_XCC_ID, 0, 4)
	s_waitcnt vmcnt(0) expcnt(0) lgkmcnt(0)
	ds_read_b32 v2, v0
	s_add_i32 s7, 0, 0x25fd4
	v_mov_b32_e32 v0, s7
	ds_read_b32 v0, v0
	s_and_b32 s56, s6, 15
	s_waitcnt lgkmcnt(1)
	v_cmp_ne_u32_e32 vcc, 0, v2
	s_cbranch_vccnz .LBB0_219
	s_add_u32 s6, s76, 0x8200
	s_addc_u32 s7, s77, 0
	s_add_u32 s8, s76, 0x8400
	s_addc_u32 s9, s77, 0
	s_add_u32 s10, s76, 0x8500
	s_addc_u32 s11, s77, 0
	s_add_u32 s12, s76, 0x8600
	s_addc_u32 s13, s77, 0
	s_add_u32 s14, s76, 0x8700
	s_addc_u32 s15, s77, 0
	s_add_u32 s16, s76, 0x8800
	s_addc_u32 s17, s77, 0
	s_add_u32 s18, s76, 0x8900
	s_addc_u32 s19, s77, 0
	s_add_u32 s20, s76, 0x8a00
	s_addc_u32 s21, s77, 0
	s_add_u32 s22, s76, 0x8b00
	s_addc_u32 s23, s77, 0
	s_add_u32 s24, s76, 0x8c00
	s_addc_u32 s25, s77, 0
	s_add_u32 s26, s76, 0x8d00
	s_addc_u32 s27, s77, 0
	s_add_u32 s28, s76, 0x8e00
	s_addc_u32 s29, s77, 0
	s_add_u32 s30, s76, 0x8f00
	s_addc_u32 s31, s77, 0
	s_add_u32 s38, s76, 0x9000
	s_addc_u32 s39, s77, 0
	s_add_u32 s42, s76, 0x9100
	s_addc_u32 s43, s77, 0
	s_add_u32 s44, s76, 0x9200
	s_addc_u32 s45, s77, 0
	s_add_u32 s48, s76, 0x9300
	s_addc_u32 s49, s77, 0
	s_mov_b32 s57, 1
	v_mov_b32_e32 v16, 0
	s_branch .LBB0_207

.LBB0_261:
	s_and_saveexec_b64 s[4:5], s[0:1]
	s_cbranch_execz .LBB0_265
	s_mov_b64 s[8:9], exec
	s_waitcnt vmcnt(23)
	v_mbcnt_lo_u32_b32 v0, s8, 0
	v_mbcnt_hi_u32_b32 v0, s9, v0
	v_cmp_eq_u32_e32 vcc, 0, v0
	s_and_saveexec_b64 s[6:7], vcc
	s_cbranch_execz .LBB0_264
	s_bcnt1_i32_b64 s8, s[8:9]
	v_mov_b32_e32 v1, s8
	s_and_b32 s100, s2, 7
	s_lshl_b32 s100, s100, 6
	s_add_i32 s100, s100, 0xb800
	s_cmp_eq_u32 s99, 0
	s_cselect_b32 s100, 0, s100
	v_mov_b32_e32 v2, s100
	global_atomic_add v1, v2, v1, s[76:77] sc0

.LBB0_265:
	s_or_b64 exec, exec, s[4:5]
	s_waitcnt lgkmcnt(0)
	s_barrier
	s_waitcnt vmcnt(23)
	ds_read_b32 v0, v190
	s_mov_b64 s[4:5], -1
	s_waitcnt lgkmcnt(0)
	s_barrier
	v_readfirstlane_b32 s39, v0
	s_cmp_eq_u32 s99, 0
	s_cbranch_scc1 .Lq_mapped
	s_and_b32 s100, s2, 7
	s_cmp_lt_u32 s39, 12
	s_cbranch_scc0 .Lq_m1
	s_mul_i32 s101, s100, 12
	s_add_i32 s39, s39, s101
	s_branch .Lq_mapped
.Lq_m1:
	s_cmp_lt_u32 s39, 16
	s_cbranch_scc0 .Lq_m2
	s_lshl_b32 s101, s100, 2
	s_add_i32 s39, s39, s101
	s_add_i32 s39, s39, 84
	s_branch .Lq_mapped
.Lq_m2:
	s_cmp_lt_u32 s39, 32
	s_cbranch_scc0 .Lq_m3
	s_sub_i32 s39, s39, 16
	s_lshr_b32 s101, s39, 3
	s_and_b32 s39, s39, 7
	s_lshl_b32 s101, s101, 6
	s_add_i32 s39, s39, s101
	s_lshl_b32 s101, s100, 3
	s_add_i32 s39, s39, s101
	s_add_i32 s39, s39, 0x80
	s_branch .Lq_mapped
.Lq_m3:
	s_cmp_lt_u32 s39, 44
	s_cbranch_scc0 .Lq_m4
	s_mul_i32 s101, s100, 12
	s_add_i32 s39, s39, s101
	s_add_i32 s39, s39, 0xe0
	s_branch .Lq_mapped
.Lq_m4:
	s_cmp_lt_u32 s39, 0x9c
	s_cbranch_scc0 .Lq_m5
	s_sub_i32 s39, s39, 44
	s_lshr_b32 s101, s39, 3
	s_and_b32 s39, s39, 7
	s_lshl_b32 s101, s101, 6
	s_add_i32 s39, s39, s101
	s_lshl_b32 s101, s100, 3
	s_add_i32 s39, s39, s101
	s_add_i32 s39, s39, 0x160
	s_branch .Lq_mapped
.Lq_m5:
	s_movk_i32 s39, 0x4e0
.Lq_mapped:
	s_cmpk_gt_i32 s39, 0x4df
	s_cbranch_scc1 .LBB0_260
	s_cmpk_gt_i32 s39, 0x5f
	s_cbranch_scc1 .LBB0_269
	s_andn2_b64 vcc, exec, s[4:5]
	s_cbranch_vccz .LBB0_429

.LBB0_280:
	s_waitcnt lgkmcnt(0)
	s_cmp_lg_u32 s99, 0
	s_cbranch_scc1 .Lnf_3
	buffer_inv sc1
.Lnf_3:
	s_waitcnt vmcnt(0)
.LBB0_281:
	s_or_b64 exec, exec, s[4:5]
	s_mul_i32 s4, s72, 3
	s_sub_i32 s4, s39, s4
	s_add_i32 s4, s4, 1
	s_waitcnt vmcnt(22)
	v_and_b32_e32 v36, 63, v66
	s_and_b32 s78, s4, 0xff
	s_ashr_i32 s56, s8, 6
	v_bfe_u32 v67, v66, 4, 2
	v_lshlrev_b32_e32 v0, 4, v36
	v_mov_b32_e32 v1, v99
	v_and_b32_e32 v80, 48, v66
	v_mov_b32_e32 v81, v99
	v_writelane_b32 v255, s84, 12
	s_mul_i32 s4, s72, 24
	s_waitcnt vmcnt(19)
	v_mov_b32_e32 v8, 0
	v_lshl_add_u64 v[32:33], s[48:49], 0, v[0:1]
	v_lshlrev_b32_e32 v68, 2, v67
	v_writelane_b32 v255, s85, 13
	v_lshl_add_u64 v[34:35], s[84:85], 0, v[80:81]
	s_add_i32 s4, s56, s4
	s_mul_i32 s54, s72, 0x180
	s_mov_b32 s6, s78
	v_mov_b32_e32 v9, v8
	v_mov_b32_e32 v10, v8
	v_mov_b32_e32 v11, v8
	s_waitcnt vmcnt(9)
	v_mov_b32_e32 v12, v8
	v_mov_b32_e32 v13, v8
	v_mov_b32_e32 v14, v8
	v_mov_b32_e32 v15, v8
	s_waitcnt vmcnt(8)
	v_mov_b32_e32 v4, v8
	v_mov_b32_e32 v5, v8
	v_mov_b32_e32 v6, v8
	v_mov_b32_e32 v7, v8
	v_mov_b32_e32 v0, v8
	v_mov_b32_e32 v1, v8
	v_mov_b32_e32 v2, v8
	v_mov_b32_e32 v3, v8
	v_mov_b32_e32 v28, v8
	v_mov_b32_e32 v29, v8
	v_mov_b32_e32 v30, v8
	v_mov_b32_e32 v31, v8
	v_mov_b32_e32 v24, v8
	v_mov_b32_e32 v25, v8
	v_mov_b32_e32 v26, v8
	v_mov_b32_e32 v27, v8
	v_mov_b32_e32 v20, v8
	v_mov_b32_e32 v21, v8
	v_mov_b32_e32 v22, v8
	v_mov_b32_e32 v23, v8
	v_mov_b32_e32 v16, v8
	v_mov_b32_e32 v17, v8
	v_mov_b32_e32 v18, v8
	v_mov_b32_e32 v19, v8
	s_waitcnt lgkmcnt(0)
	s_barrier

.LBB0_435:
	s_waitcnt vmcnt(0)
	v_cmp_eq_u32_e32 vcc, 0, v51
	s_waitcnt lgkmcnt(0)
	s_barrier
	s_and_saveexec_b64 s[4:5], vcc
	s_cbranch_execz .LBB0_438
	s_mov_b64 s[6:7], exec
	v_mbcnt_lo_u32_b32 v0, s6, 0
	s_cmp_lg_u32 s99, 0
	s_cbranch_scc1 .Lnf_4
	buffer_wbl2 sc1
.Lnf_4:
	s_waitcnt vmcnt(0)
	s_waitcnt vmcnt(0)
	v_mbcnt_hi_u32_b32 v0, s7, v0
	v_cmp_eq_u32_e32 vcc, 0, v0
	s_and_b64 s[8:9], exec, vcc
	s_mov_b64 exec, s[8:9]
	s_cbranch_execz .LBB0_438
	s_bcnt1_i32_b64 s8, s[6:7]
	s_lshl_b32 s6, s12, 6
	s_ashr_i32 s7, s6, 31
	s_lshl_b64 s[6:7], s[6:7], 2
	s_add_u32 s6, s76, s6
	s_addc_u32 s7, s77, s7
	v_mov_b32_e32 v0, s8
	global_atomic_add v99, v0, s[6:7] offset:1024

.LBB0_537:
	s_cmp_eq_u32 s99, 0
	s_cbranch_scc1 .Lfull_2
	v_readlane_b32 s54, v255, 1
	v_readlane_b32 s27, v255, 0
	v_readlane_b32 s55, v255, 2
	s_waitcnt vmcnt(0) lgkmcnt(0)
	s_barrier
	s_cmp_lg_u32 s33, 0
	s_cbranch_scc1 .Lls_join_2
	s_mov_b64 exec, 1
	s_add_i32 s98, 0, 0x25fd0
	v_mov_b32_e32 v0, s98
	ds_read_b32 v2, v0
	s_getreg_b32 s98, hwreg(HW_REG_XCC_ID, 0, 4)
	s_and_b32 s98, s98, 15
	s_lshl_b32 s98, s98, 8
	s_add_u32 s100, s76, s98
	s_addc_u32 s101, s77, 0
	v_mov_b32_e32 v0, 0xc000
	v_mov_b32_e32 v1, 1
	global_atomic_add v0, v1, s[100:101]
	s_waitcnt lgkmcnt(0)
	v_mul_lo_u32 v2, v2, 2
	s_mov_b32 s98, 0

.Lls_spun_2:
	buffer_inv sc1
	s_waitcnt vmcnt(0)
	s_mov_b64 exec, -1
.Lls_join_2:
	s_barrier
	s_branch .LBB0_590
.Lfull_2:
	s_waitcnt vmcnt(23)
	v_mov_b32_e32 v0, 0
	s_nop 0
	v_mbcnt_lo_u32_b32 v0, -1, v0
	v_mbcnt_hi_u32_b32 v0, -1, v0
	v_add_u32_e32 v0, s33, v0
	s_waitcnt vmcnt(0)
	s_nop 0
	v_cmp_eq_u32_e32 vcc, 0, v0
	s_barrier
	s_and_saveexec_b64 s[0:1], vcc
	v_readlane_b32 s54, v255, 1
	v_readlane_b32 s27, v255, 0
	v_readlane_b32 s55, v255, 2
	s_cbranch_execz .LBB0_589
	s_add_i32 s5, 0, 0x25fd0
	v_mov_b32_e32 v0, s5
	s_getreg_b32 s4, hwreg(HW_REG_XCC_ID, 0, 4)
	s_waitcnt vmcnt(0) expcnt(0) lgkmcnt(0)
	ds_read_b32 v2, v0
	s_add_i32 s5, 0, 0x25fd4
	v_mov_b32_e32 v0, s5
	ds_read_b32 v0, v0
	s_and_b32 s42, s4, 15
	s_waitcnt lgkmcnt(1)
	v_cmp_ne_u32_e32 vcc, 0, v2
	s_cbranch_vccnz .LBB0_553
	s_add_u32 s4, s76, 0x8200
	s_addc_u32 s5, s77, 0
	s_add_u32 s6, s76, 0x8400
	s_addc_u32 s7, s77, 0
	s_add_u32 s8, s76, 0x8500
	s_addc_u32 s9, s77, 0
	s_add_u32 s10, s76, 0x8600
	s_addc_u32 s11, s77, 0
	s_add_u32 s12, s76, 0x8700
	s_addc_u32 s13, s77, 0
	s_add_u32 s14, s76, 0x8800
	s_addc_u32 s15, s77, 0
	s_add_u32 s16, s76, 0x8900
	s_addc_u32 s17, s77, 0
	s_add_u32 s18, s76, 0x8a00
	s_addc_u32 s19, s77, 0
	s_add_u32 s20, s76, 0x8b00
	s_addc_u32 s21, s77, 0
	s_add_u32 s22, s76, 0x8c00
	s_addc_u32 s23, s77, 0
	s_add_u32 s24, s76, 0x8d00
	s_addc_u32 s25, s77, 0
	s_add_u32 s26, s76, 0x8e00
	s_addc_u32 s27, s77, 0
	s_add_u32 s28, s76, 0x8f00
	s_addc_u32 s29, s77, 0
	s_add_u32 s30, s76, 0x9000
	s_addc_u32 s31, s77, 0
	s_add_u32 s38, s76, 0x9100
	s_addc_u32 s39, s77, 0
	s_add_u32 s44, s76, 0x9200
	s_addc_u32 s45, s77, 0
	s_add_u32 s46, s76, 0x9300
	s_addc_u32 s47, s77, 0
	s_mov_b32 s43, 1
	v_mov_b32_e32 v16, 0
	s_branch .LBB0_541

.LBB0_925:
	s_cmp_eq_u32 s99, 0
	s_cbranch_scc1 .Lfull_6
	s_waitcnt vmcnt(0) lgkmcnt(0)
	s_barrier
	s_cmp_lg_u32 s33, 0
	s_cbranch_scc1 .Lls_join_6
	s_mov_b64 exec, 1
	s_add_i32 s98, 0, 0x25fd0
	v_mov_b32_e32 v0, s98
	ds_read_b32 v2, v0
	s_getreg_b32 s98, hwreg(HW_REG_XCC_ID, 0, 4)
	s_and_b32 s98, s98, 15
	s_lshl_b32 s98, s98, 8
	s_add_u32 s100, s76, s98
	s_addc_u32 s101, s77, 0
	v_mov_b32_e32 v0, 0xc000
	v_mov_b32_e32 v1, 1
	global_atomic_add v0, v1, s[100:101]
	s_waitcnt lgkmcnt(0)
	v_mul_lo_u32 v2, v2, 5
	s_mov_b32 s98, 0
